# v8 + FoX step-A PV block: V fragment reads issued up to 3 MFMAs ahead into dead score registers, counted waits
# speedup vs baseline: 1.0150x; 1.0052x over previous
.LBB0_343:
	v_sub_f32_e32 v48, v48, v236
	v_exp_f32_e32 v198, v48
	v_sub_f32_e32 v48, v49, v236
	v_exp_f32_e32 v199, v48
	v_sub_f32_e32 v48, v50, v236
	v_exp_f32_e32 v200, v48
	v_sub_f32_e32 v48, v51, v236
	v_exp_f32_e32 v201, v48
	v_sub_f32_e32 v48, v52, v236
	v_exp_f32_e32 v202, v48
	v_sub_f32_e32 v48, v53, v236
	v_exp_f32_e32 v203, v48
	v_sub_f32_e32 v48, v54, v236
	v_exp_f32_e32 v204, v48
	v_sub_f32_e32 v48, v55, v236
	v_exp_f32_e32 v205, v48
	v_sub_f32_e32 v48, v56, v236
	v_exp_f32_e32 v206, v48
	v_sub_f32_e32 v48, v57, v236
	v_sub_f32_e32 v32, v32, v236
	v_exp_f32_e32 v207, v48
	v_sub_f32_e32 v48, v58, v236
	v_exp_f32_e32 v214, v32
	v_sub_f32_e32 v32, v33, v236
	v_exp_f32_e32 v208, v48
	v_sub_f32_e32 v48, v59, v236
	v_exp_f32_e32 v215, v32
	v_sub_f32_e32 v32, v34, v236
	v_exp_f32_e32 v209, v48
	v_sub_f32_e32 v48, v60, v236
	v_exp_f32_e32 v216, v32
	v_sub_f32_e32 v32, v35, v236
	v_exp_f32_e32 v210, v48
	v_sub_f32_e32 v48, v61, v236
	v_exp_f32_e32 v217, v32
	v_sub_f32_e32 v32, v36, v236
	v_exp_f32_e32 v211, v48
	v_sub_f32_e32 v48, v62, v236
	v_exp_f32_e32 v218, v32
	v_sub_f32_e32 v32, v37, v236
	v_exp_f32_e32 v212, v48
	v_sub_f32_e32 v48, v63, v236
	v_exp_f32_e32 v219, v32
	v_sub_f32_e32 v32, v38, v236
	v_exp_f32_e32 v213, v48
	v_exp_f32_e32 v220, v32
	ds_read_b64_tr_b16 v[52:53], v194 offset:16640
	ds_read_b64_tr_b16 v[54:55], v194 offset:17152
	ds_read_b64_tr_b16 v[56:57], v194 offset:20800
	ds_read_b64_tr_b16 v[58:59], v194 offset:21312
	ds_read_b64_tr_b16 v[60:61], v194 offset:17664
	ds_read_b64_tr_b16 v[62:63], v194 offset:18176
	v_cvt_pk_bf16_f32 v32, v198, v199
	v_cvt_pk_bf16_f32 v33, v200, v201
	v_cvt_pk_bf16_f32 v34, v202, v203
	v_cvt_pk_bf16_f32 v35, v204, v205
	v_sub_f32_e32 v36, v39, v236
	v_exp_f32_e32 v221, v36
	v_sub_f32_e32 v36, v40, v236
	v_exp_f32_e32 v222, v36
	s_waitcnt lgkmcnt(4)
	v_mfma_f32_32x32x16_bf16 v[0:15], v[32:35], v[52:55], v[0:15]
	ds_read_b64_tr_b16 v[52:53], v194 offset:21824
	ds_read_b64_tr_b16 v[54:55], v194 offset:22336
	v_cvt_pk_bf16_f32 v48, v206, v207
	v_cvt_pk_bf16_f32 v49, v208, v209
	v_cvt_pk_bf16_f32 v50, v210, v211
	v_cvt_pk_bf16_f32 v51, v212, v213
	v_sub_f32_e32 v40, v41, v236
	v_exp_f32_e32 v223, v40
	v_sub_f32_e32 v40, v45, v236
	s_waitcnt lgkmcnt(4)
	v_mfma_f32_32x32x16_bf16 v[16:31], v[32:35], v[56:59], v[16:31]
	ds_read_b64_tr_b16 v[56:57], v194 offset:18688
	ds_read_b64_tr_b16 v[58:59], v194 offset:19200
	v_sub_f32_e32 v36, v42, v236
	v_exp_f32_e32 v224, v36
	v_sub_f32_e32 v36, v43, v236
	v_exp_f32_e32 v225, v36
	v_sub_f32_e32 v36, v44, v236
	v_exp_f32_e32 v226, v36
	s_waitcnt lgkmcnt(4)
	v_mfma_f32_32x32x16_bf16 v[0:15], v[48:51], v[60:63], v[0:15]
	ds_read_b64_tr_b16 v[60:61], v194 offset:22848
	ds_read_b64_tr_b16 v[62:63], v194 offset:23360
	v_cvt_pk_bf16_f32 v36, v214, v215
	v_cvt_pk_bf16_f32 v37, v216, v217
	v_cvt_pk_bf16_f32 v38, v218, v219
	v_cvt_pk_bf16_f32 v39, v220, v221
	v_exp_f32_e32 v227, v40
	v_sub_f32_e32 v40, v46, v236
	s_waitcnt lgkmcnt(4)
	v_mfma_f32_32x32x16_bf16 v[16:31], v[48:51], v[52:55], v[16:31]
	ds_read_b64_tr_b16 v[52:53], v194 offset:19712
	ds_read_b64_tr_b16 v[54:55], v194 offset:20224
	v_exp_f32_e32 v228, v40
	v_sub_f32_e32 v40, v47, v236
	v_exp_f32_e32 v229, v40
	v_cvt_pk_bf16_f32 v40, v222, v223
	v_cvt_pk_bf16_f32 v41, v224, v225
	v_cvt_pk_bf16_f32 v42, v226, v227
	s_waitcnt lgkmcnt(4)
	v_mfma_f32_32x32x16_bf16 v[0:15], v[36:39], v[56:59], v[0:15]
	ds_read_b64_tr_b16 v[56:57], v194 offset:23872
	ds_read_b64_tr_b16 v[58:59], v194 offset:24384
	v_cvt_pk_bf16_f32 v43, v228, v229
	s_andn2_b64 vcc, exec, s[4:5]
	s_waitcnt lgkmcnt(4)
	v_mfma_f32_32x32x16_bf16 v[16:31], v[36:39], v[60:63], v[16:31]
	s_waitcnt lgkmcnt(2)
	v_mfma_f32_32x32x16_bf16 v[0:15], v[40:43], v[52:55], v[0:15]
	s_waitcnt lgkmcnt(0)
	v_mfma_f32_32x32x16_bf16 v[16:31], v[40:43], v[56:59], v[16:31]
	v_cndmask_b32_e64 v33, 0, 1, s[4:5]
	v_add_u32_e32 v32, s63, v138
	v_cmp_ne_u32_e64 s[48:49], 1, v33
	s_waitcnt vmcnt(0)
	ds_write_b128 v32, v[100:103] offset:16640
	s_cbranch_vccnz .LBB0_345
	v_add_u32_e32 v32, s64, v109
	ds_write_b128 v32, v[96:99]
